# stack: P0 rmsnorm gain hoist + sample_norm gain preload (P2/P10 tails) + LRU unit prologue LDS-fill loads batched (P5/P6)
# speedup vs baseline: 1.0117x; 1.0036x over previous
; #define LAS __attribute__((address_space(3)))
; #define TIDW(wv) ((wv) * 64 + lane_id())
; template <int PASS> __device__ __forceinline__ void lru_cu_unit(const Args& a, LAS unsigned char* lds, int u, int wave) {
;     ...
;     { const u32x4* src = (const u32x4*)(ws + WS_LW + (size_t)n * 33280); LAS u32x4* dst = (LAS u32x4*)(lds + L2_LW);
;       for (int i = TIDW(wave); i < 2080; i += 512) dst[i] = src[i]; }
.LBB0_826:
	global_load_dwordx4 v[6:9], v[2:3], off
	v_lshl_add_u64 v[2:3], v[2:3], 0, s[14:15]
	global_load_dwordx4 v[10:13], v[2:3], off
	v_lshl_add_u64 v[2:3], v[2:3], 0, s[14:15]
	global_load_dwordx4 v[14:17], v[2:3], off
	v_lshl_add_u64 v[2:3], v[2:3], 0, s[14:15]
	global_load_dwordx4 v[18:21], v[2:3], off
	v_lshl_add_u64 v[2:3], v[2:3], 0, s[14:15]
	v_add_u32_e32 v4, 0x800, v4
	v_cmp_ge_i32_e32 vcc, s29, v4
	s_and_saveexec_b64 s[12:13], vcc
	global_load_dwordx4 v[22:25], v[2:3], off
	s_mov_b64 exec, s[12:13]
	s_waitcnt vmcnt(0)
	ds_write_b128 v1, v[6:9]
	ds_write_b128 v1, v[10:13] offset:8192
	ds_write_b128 v1, v[14:17] offset:16384
	ds_write_b128 v1, v[18:21] offset:24576
	s_and_b64 exec, exec, vcc
	ds_write_b128 v1, v[22:25] offset:32768
	s_mov_b64 exec, s[12:13]

; #define LAS __attribute__((address_space(3)))
; #define TIDW(wv) ((wv) * 64 + lane_id())
; template <int PASS> __device__ __forceinline__ void lru_cu_unit(const Args& a, LAS unsigned char* lds, int u, int wave) {
;     ...
;     { const u32x4* src = (const u32x4*)(ws + WS_LW + (size_t)n * 33280); LAS u32x4* dst = (LAS u32x4*)(lds + L2_LW);
;       for (int i = TIDW(wave); i < 2080; i += 512) dst[i] = src[i]; }
.LBB0_1007:
	global_load_dwordx4 v[6:9], v[2:3], off
	v_lshl_add_u64 v[2:3], v[2:3], 0, s[28:29]
	global_load_dwordx4 v[10:13], v[2:3], off
	v_lshl_add_u64 v[2:3], v[2:3], 0, s[28:29]
	global_load_dwordx4 v[14:17], v[2:3], off
	v_lshl_add_u64 v[2:3], v[2:3], 0, s[28:29]
	global_load_dwordx4 v[18:21], v[2:3], off
	v_lshl_add_u64 v[2:3], v[2:3], 0, s[28:29]
	v_add_u32_e32 v4, 0x800, v4
	v_cmp_ge_i32_e32 vcc, s62, v4
	s_and_saveexec_b64 s[8:9], vcc
	global_load_dwordx4 v[22:25], v[2:3], off
	s_mov_b64 exec, s[8:9]
	s_waitcnt vmcnt(0)
	ds_write_b128 v1, v[6:9]
	ds_write_b128 v1, v[10:13] offset:8192
	ds_write_b128 v1, v[14:17] offset:16384
	ds_write_b128 v1, v[18:21] offset:24576
	s_and_b64 exec, exec, vcc
	ds_write_b128 v1, v[22:25] offset:32768
	s_mov_b64 exec, s[8:9]
